# as previous no-duplicate-wait version, with one s_barrier moved above an m0/address pair so the MFMA SrcC->VALU write distance is 3 states again (hazard-clean)
# speedup vs baseline: 1.0016x; 1.0005x over previous
.LBB0_173:
	s_add_u32 s64, s62, 0x100
	s_addc_u32 s65, s63, 0
	s_add_i32 s34, 0, 0x10000
	v_add_u32_e32 v108, s34, v196
	ds_read_b128 v[96:99], v108
	ds_read_b128 v[100:103], v108 offset:1024
	ds_read_b128 v[104:107], v108 offset:2048
	ds_read_b128 v[158:161], v108 offset:3072
	s_cmp_eq_u32 s83, 28
	s_cselect_b32 s69, s57, s65
	s_cselect_b32 s68, s71, s64
	s_cselect_b32 s67, s55, s82
	s_cselect_b32 s66, s80, s81
	v_lshl_add_u64 v[108:109], s[62:63], 0, v[154:155]
	s_add_i32 m0, s44, 0xc000
	ds_read_b128 v[162:165], v207
	ds_read_b128 v[166:169], v207 offset:1024
	ds_read_b128 v[170:173], v207 offset:2048
	ds_read_b128 v[180:183], v207 offset:3072
	ds_read_b128 v[184:187], v207 offset:4096
	ds_read_b128 v[188:191], v207 offset:5120
	ds_read_b128 v[192:195], v207 offset:6144
	ds_read_b128 v[198:201], v207 offset:7168
	global_load_lds_dwordx4 v[108:109], off
	v_lshl_add_u64 v[108:109], s[62:63], 0, v[156:157]
	s_add_i32 m0, s44, 0xe000
	s_nop 0
	global_load_lds_dwordx4 v[108:109], off
	s_waitcnt lgkmcnt(8)
	s_barrier
	s_waitcnt lgkmcnt(0)
	v_mfma_f32_16x16x32_bf16 v[138:141], v[96:99], v[162:165], v[138:141]
	v_mfma_f32_16x16x32_bf16 v[60:63], v[104:107], v[162:165], v[60:63]
	v_mfma_f32_16x16x32_bf16 v[134:137], v[96:99], v[170:173], v[134:137]
	v_mfma_f32_16x16x32_bf16 v[56:59], v[104:107], v[170:173], v[56:59]
	v_mfma_f32_16x16x32_bf16 v[130:133], v[96:99], v[184:187], v[130:133]
	v_mfma_f32_16x16x32_bf16 v[52:55], v[104:107], v[184:187], v[52:55]
	v_mfma_f32_16x16x32_bf16 v[126:129], v[96:99], v[192:195], v[126:129]
	v_mfma_f32_16x16x32_bf16 v[48:51], v[104:107], v[192:195], v[48:51]
	v_mfma_f32_16x16x32_bf16 v[138:141], v[100:103], v[166:169], v[138:141]
	v_mfma_f32_16x16x32_bf16 v[60:63], v[158:161], v[166:169], v[60:63]
	v_mfma_f32_16x16x32_bf16 v[134:137], v[100:103], v[180:183], v[134:137]
	v_mfma_f32_16x16x32_bf16 v[56:59], v[158:161], v[180:183], v[56:59]
	v_mfma_f32_16x16x32_bf16 v[130:133], v[100:103], v[188:191], v[130:133]
	v_mfma_f32_16x16x32_bf16 v[52:55], v[158:161], v[188:191], v[52:55]
	v_mfma_f32_16x16x32_bf16 v[126:129], v[100:103], v[198:201], v[126:129]
	v_mfma_f32_16x16x32_bf16 v[48:51], v[158:161], v[198:201], v[48:51]
	s_barrier
	s_add_i32 s35, 0, 0x14000
	s_add_i32 s34, s34, s39
	v_add_u32_e32 v108, s35, v196
	v_lshl_add_u64 v[174:175], s[66:67], 0, v[146:147]
	s_mov_b32 m0, s34
	ds_read_b128 v[208:211], v108
	ds_read_b128 v[212:215], v108 offset:1024
	ds_read_b128 v[216:219], v108 offset:2048
	ds_read_b128 v[220:223], v108 offset:3072
	global_load_lds_dwordx4 v[174:175], off
	v_lshl_add_u64 v[224:225], s[66:67], 0, v[142:143]
	s_add_i32 m0, s34, 0x2000
	s_nop 0
	global_load_lds_dwordx4 v[224:225], off
	s_barrier
	s_waitcnt lgkmcnt(0)
	v_mfma_f32_16x16x32_bf16 v[122:125], v[208:211], v[162:165], v[122:125]
	v_mfma_f32_16x16x32_bf16 v[44:47], v[216:219], v[162:165], v[44:47]
	v_mfma_f32_16x16x32_bf16 v[114:117], v[208:211], v[170:173], v[114:117]
	v_mfma_f32_16x16x32_bf16 v[36:39], v[216:219], v[170:173], v[36:39]
	v_mfma_f32_16x16x32_bf16 v[118:121], v[208:211], v[184:187], v[118:121]
	v_mfma_f32_16x16x32_bf16 v[40:43], v[216:219], v[184:187], v[40:43]
	v_mfma_f32_16x16x32_bf16 v[108:111], v[208:211], v[192:195], v[110:113]
	v_mfma_f32_16x16x32_bf16 v[32:35], v[216:219], v[192:195], v[32:35]
	v_mfma_f32_16x16x32_bf16 v[122:125], v[212:215], v[166:169], v[122:125]
	v_mfma_f32_16x16x32_bf16 v[44:47], v[220:223], v[166:169], v[44:47]
	v_mfma_f32_16x16x32_bf16 v[114:117], v[212:215], v[180:183], v[114:117]
	v_mfma_f32_16x16x32_bf16 v[36:39], v[220:223], v[180:183], v[36:39]
	v_mfma_f32_16x16x32_bf16 v[118:121], v[212:215], v[188:191], v[118:121]
	v_mfma_f32_16x16x32_bf16 v[40:43], v[220:223], v[188:191], v[40:43]
	v_mfma_f32_16x16x32_bf16 v[108:111], v[212:215], v[198:201], v[108:111]
	v_mfma_f32_16x16x32_bf16 v[32:35], v[220:223], v[198:201], v[32:35]
	s_mov_b32 m0, s44
	v_lshl_add_u64 v[226:227], s[68:69], 0, v[148:149]
	s_barrier
	ds_read_b128 v[162:165], v207 offset:16384
	ds_read_b128 v[166:169], v207 offset:17408
	ds_read_b128 v[170:173], v207 offset:18432
	ds_read_b128 v[180:183], v207 offset:19456
	ds_read_b128 v[184:187], v207 offset:20480
	ds_read_b128 v[188:191], v207 offset:21504
	ds_read_b128 v[192:195], v207 offset:22528
	ds_read_b128 v[198:201], v207 offset:23552
	global_load_lds_dwordx4 v[226:227], off
	v_lshl_add_u64 v[228:229], s[68:69], 0, v[144:145]
	s_mov_b32 m0, s72
	s_nop 0
	global_load_lds_dwordx4 v[228:229], off
	s_barrier
	s_waitcnt lgkmcnt(0)
	v_mfma_f32_16x16x32_bf16 v[92:95], v[96:99], v[162:165], v[92:95]
	v_mfma_f32_16x16x32_bf16 v[28:31], v[104:107], v[162:165], v[28:31]
	v_mfma_f32_16x16x32_bf16 v[88:91], v[96:99], v[170:173], v[88:91]
	v_mfma_f32_16x16x32_bf16 v[24:27], v[104:107], v[170:173], v[24:27]
	v_mfma_f32_16x16x32_bf16 v[84:87], v[96:99], v[184:187], v[84:87]
	v_mfma_f32_16x16x32_bf16 v[20:23], v[104:107], v[184:187], v[20:23]
	v_mfma_f32_16x16x32_bf16 v[80:83], v[96:99], v[192:195], v[80:83]
	v_mfma_f32_16x16x32_bf16 v[16:19], v[104:107], v[192:195], v[16:19]
	v_mfma_f32_16x16x32_bf16 v[92:95], v[100:103], v[166:169], v[92:95]
	v_mfma_f32_16x16x32_bf16 v[28:31], v[158:161], v[166:169], v[28:31]
	v_mfma_f32_16x16x32_bf16 v[88:91], v[100:103], v[180:183], v[88:91]
	v_mfma_f32_16x16x32_bf16 v[24:27], v[158:161], v[180:183], v[24:27]
	v_mfma_f32_16x16x32_bf16 v[84:87], v[100:103], v[188:191], v[84:87]
	v_mfma_f32_16x16x32_bf16 v[20:23], v[158:161], v[188:191], v[20:23]
	v_mfma_f32_16x16x32_bf16 v[80:83], v[100:103], v[198:201], v[80:83]
	v_mfma_f32_16x16x32_bf16 v[16:19], v[158:161], v[198:201], v[16:19]
	s_barrier
	s_add_u32 s62, s66, 0x80000
	s_addc_u32 s63, s67, 0
	s_add_i32 s34, s35, s39
	v_lshl_add_u64 v[96:97], s[62:63], 0, v[146:147]
	s_mov_b32 m0, s34
	s_nop 0
	global_load_lds_dwordx4 v[96:97], off
	v_lshl_add_u64 v[96:97], s[62:63], 0, v[142:143]
	s_add_i32 m0, s34, 0x2000
	s_nop 0
	global_load_lds_dwordx4 v[96:97], off
	s_waitcnt vmcnt(6)
	s_barrier
	v_mfma_f32_16x16x32_bf16 v[76:79], v[208:211], v[162:165], v[76:79]
	v_mfma_f32_16x16x32_bf16 v[12:15], v[216:219], v[162:165], v[12:15]
	v_mfma_f32_16x16x32_bf16 v[68:71], v[208:211], v[170:173], v[68:71]
	v_mfma_f32_16x16x32_bf16 v[4:7], v[216:219], v[170:173], v[4:7]
	v_mfma_f32_16x16x32_bf16 v[72:75], v[208:211], v[184:187], v[72:75]
	v_mfma_f32_16x16x32_bf16 v[8:11], v[216:219], v[184:187], v[8:11]
	v_mfma_f32_16x16x32_bf16 v[64:67], v[208:211], v[192:195], v[64:67]
	v_mfma_f32_16x16x32_bf16 v[0:3], v[216:219], v[192:195], v[0:3]
	v_mfma_f32_16x16x32_bf16 v[76:79], v[212:215], v[166:169], v[76:79]
	v_mfma_f32_16x16x32_bf16 v[12:15], v[220:223], v[166:169], v[12:15]
	v_mfma_f32_16x16x32_bf16 v[68:71], v[212:215], v[180:183], v[68:71]
	v_mfma_f32_16x16x32_bf16 v[4:7], v[220:223], v[180:183], v[4:7]
	v_mfma_f32_16x16x32_bf16 v[72:75], v[212:215], v[188:191], v[72:75]
	v_mfma_f32_16x16x32_bf16 v[8:11], v[220:223], v[188:191], v[8:11]
	v_mfma_f32_16x16x32_bf16 v[64:67], v[212:215], v[198:201], v[64:67]
	v_mfma_f32_16x16x32_bf16 v[0:3], v[220:223], v[198:201], v[0:3]
	s_add_i32 s34, 0, 0x18000
	v_add_u32_e32 v112, s34, v196
	s_barrier
	ds_read_b128 v[96:99], v112
	ds_read_b128 v[100:103], v112 offset:1024
	ds_read_b128 v[104:107], v112 offset:2048
	ds_read_b128 v[158:161], v112 offset:3072
	s_add_u32 s62, s68, 0x80000
	s_addc_u32 s63, s69, 0
	s_mov_b32 m0, s73
	v_lshl_add_u64 v[112:113], s[62:63], 0, v[148:149]
	ds_read_b128 v[162:165], v207 offset:32768
	ds_read_b128 v[166:169], v207 offset:33792
	ds_read_b128 v[170:173], v207 offset:34816
	ds_read_b128 v[180:183], v207 offset:35840
	ds_read_b128 v[184:187], v207 offset:36864
	ds_read_b128 v[188:191], v207 offset:37888
	ds_read_b128 v[192:195], v207 offset:38912
	ds_read_b128 v[198:201], v207 offset:39936
	global_load_lds_dwordx4 v[112:113], off
	v_lshl_add_u64 v[112:113], s[62:63], 0, v[144:145]
	s_mov_b32 m0, s74
	s_nop 0
	global_load_lds_dwordx4 v[112:113], off
	s_waitcnt lgkmcnt(8)
	s_barrier
	s_waitcnt lgkmcnt(0)
	v_mfma_f32_16x16x32_bf16 v[138:141], v[96:99], v[162:165], v[138:141]
	v_mfma_f32_16x16x32_bf16 v[60:63], v[104:107], v[162:165], v[60:63]
	v_mfma_f32_16x16x32_bf16 v[134:137], v[96:99], v[170:173], v[134:137]
	v_mfma_f32_16x16x32_bf16 v[56:59], v[104:107], v[170:173], v[56:59]
	v_mfma_f32_16x16x32_bf16 v[130:133], v[96:99], v[184:187], v[130:133]
	v_mfma_f32_16x16x32_bf16 v[52:55], v[104:107], v[184:187], v[52:55]
	v_mfma_f32_16x16x32_bf16 v[126:129], v[96:99], v[192:195], v[126:129]
	v_mfma_f32_16x16x32_bf16 v[48:51], v[104:107], v[192:195], v[48:51]
	v_mfma_f32_16x16x32_bf16 v[138:141], v[100:103], v[166:169], v[138:141]
	v_mfma_f32_16x16x32_bf16 v[60:63], v[158:161], v[166:169], v[60:63]
	v_mfma_f32_16x16x32_bf16 v[134:137], v[100:103], v[180:183], v[134:137]
	v_mfma_f32_16x16x32_bf16 v[56:59], v[158:161], v[180:183], v[56:59]
	v_mfma_f32_16x16x32_bf16 v[130:133], v[100:103], v[188:191], v[130:133]
	v_mfma_f32_16x16x32_bf16 v[52:55], v[158:161], v[188:191], v[52:55]
	v_mfma_f32_16x16x32_bf16 v[126:129], v[100:103], v[198:201], v[126:129]
	v_mfma_f32_16x16x32_bf16 v[48:51], v[158:161], v[198:201], v[48:51]
	s_barrier
	s_add_i32 s35, 0, 0x1c000
	v_add_u32_e32 v112, s35, v196
	s_add_i32 s34, s34, s39
	ds_read_b128 v[208:211], v112
	ds_read_b128 v[212:215], v112 offset:1024
	ds_read_b128 v[216:219], v112 offset:2048
	ds_read_b128 v[220:223], v112 offset:3072
	v_lshl_add_u64 v[112:113], v[174:175], 0, s[40:41]
	s_mov_b32 m0, s34
	s_nop 0
	global_load_lds_dwordx4 v[112:113], off
	v_lshl_add_u64 v[112:113], v[224:225], 0, s[40:41]
	s_add_i32 m0, s34, 0x2000
	s_nop 0
	global_load_lds_dwordx4 v[112:113], off
	s_barrier
	s_waitcnt lgkmcnt(0)
	v_mfma_f32_16x16x32_bf16 v[122:125], v[208:211], v[162:165], v[122:125]
	v_mfma_f32_16x16x32_bf16 v[44:47], v[216:219], v[162:165], v[44:47]
	v_mfma_f32_16x16x32_bf16 v[112:115], v[208:211], v[170:173], v[114:117]
	v_mfma_f32_16x16x32_bf16 v[36:39], v[216:219], v[170:173], v[36:39]
	v_mfma_f32_16x16x32_bf16 v[118:121], v[208:211], v[184:187], v[118:121]
	v_mfma_f32_16x16x32_bf16 v[40:43], v[216:219], v[184:187], v[40:43]
	v_mfma_f32_16x16x32_bf16 v[108:111], v[208:211], v[192:195], v[108:111]
	v_mfma_f32_16x16x32_bf16 v[32:35], v[216:219], v[192:195], v[32:35]
	v_mfma_f32_16x16x32_bf16 v[122:125], v[212:215], v[166:169], v[122:125]
	v_mfma_f32_16x16x32_bf16 v[44:47], v[220:223], v[166:169], v[44:47]
	v_mfma_f32_16x16x32_bf16 v[114:117], v[212:215], v[180:183], v[112:115]
	v_mfma_f32_16x16x32_bf16 v[36:39], v[220:223], v[180:183], v[36:39]
	v_mfma_f32_16x16x32_bf16 v[118:121], v[212:215], v[188:191], v[118:121]
	v_mfma_f32_16x16x32_bf16 v[40:43], v[220:223], v[188:191], v[40:43]
	v_mfma_f32_16x16x32_bf16 v[110:113], v[212:215], v[198:201], v[108:111]
	v_mfma_f32_16x16x32_bf16 v[32:35], v[220:223], v[198:201], v[32:35]
	s_barrier
	s_mov_b32 m0, s76
	v_lshl_add_u64 v[108:109], v[226:227], 0, s[40:41]
	ds_read_b128 v[162:165], v207 offset:49152
	ds_read_b128 v[166:169], v207 offset:50176
	ds_read_b128 v[170:173], v207 offset:51200
	ds_read_b128 v[180:183], v207 offset:52224
	ds_read_b128 v[184:187], v207 offset:53248
	ds_read_b128 v[188:191], v207 offset:54272
	ds_read_b128 v[192:195], v207 offset:55296
	ds_read_b128 v[198:201], v207 offset:56320
	global_load_lds_dwordx4 v[108:109], off
	v_lshl_add_u64 v[108:109], v[228:229], 0, s[40:41]
	s_mov_b32 m0, s77
	s_nop 0
	global_load_lds_dwordx4 v[108:109], off
	s_barrier
	s_waitcnt lgkmcnt(0)
	v_mfma_f32_16x16x32_bf16 v[92:95], v[96:99], v[162:165], v[92:95]
	v_mfma_f32_16x16x32_bf16 v[28:31], v[104:107], v[162:165], v[28:31]
	v_mfma_f32_16x16x32_bf16 v[88:91], v[96:99], v[170:173], v[88:91]
	v_mfma_f32_16x16x32_bf16 v[24:27], v[104:107], v[170:173], v[24:27]
	v_mfma_f32_16x16x32_bf16 v[84:87], v[96:99], v[184:187], v[84:87]
	v_mfma_f32_16x16x32_bf16 v[20:23], v[104:107], v[184:187], v[20:23]
	v_mfma_f32_16x16x32_bf16 v[80:83], v[96:99], v[192:195], v[80:83]
	v_mfma_f32_16x16x32_bf16 v[16:19], v[104:107], v[192:195], v[16:19]
	v_mfma_f32_16x16x32_bf16 v[92:95], v[100:103], v[166:169], v[92:95]
	v_mfma_f32_16x16x32_bf16 v[28:31], v[158:161], v[166:169], v[28:31]
	v_mfma_f32_16x16x32_bf16 v[88:91], v[100:103], v[180:183], v[88:91]
	v_mfma_f32_16x16x32_bf16 v[24:27], v[158:161], v[180:183], v[24:27]
	v_mfma_f32_16x16x32_bf16 v[84:87], v[100:103], v[188:191], v[84:87]
	v_mfma_f32_16x16x32_bf16 v[20:23], v[158:161], v[188:191], v[20:23]
	v_mfma_f32_16x16x32_bf16 v[80:83], v[100:103], v[198:201], v[80:83]
	v_mfma_f32_16x16x32_bf16 v[16:19], v[158:161], v[198:201], v[16:19]
	s_barrier
	s_add_u32 s62, s66, 0x80080
	s_addc_u32 s63, s67, 0
	s_add_i32 s34, s35, s39
	v_lshl_add_u64 v[96:97], s[62:63], 0, v[146:147]
	s_mov_b32 m0, s34
	s_nop 0
	global_load_lds_dwordx4 v[96:97], off
	v_lshl_add_u64 v[96:97], s[62:63], 0, v[142:143]
	s_add_i32 m0, s34, 0x2000
	s_nop 0
	global_load_lds_dwordx4 v[96:97], off
	s_waitcnt vmcnt(6)
	s_barrier
	v_mfma_f32_16x16x32_bf16 v[76:79], v[208:211], v[162:165], v[76:79]
	v_mfma_f32_16x16x32_bf16 v[12:15], v[216:219], v[162:165], v[12:15]
	v_mfma_f32_16x16x32_bf16 v[68:71], v[208:211], v[170:173], v[68:71]
	v_mfma_f32_16x16x32_bf16 v[4:7], v[216:219], v[170:173], v[4:7]
	v_mfma_f32_16x16x32_bf16 v[72:75], v[208:211], v[184:187], v[72:75]
	v_mfma_f32_16x16x32_bf16 v[8:11], v[216:219], v[184:187], v[8:11]
	v_mfma_f32_16x16x32_bf16 v[64:67], v[208:211], v[192:195], v[64:67]
	v_mfma_f32_16x16x32_bf16 v[0:3], v[216:219], v[192:195], v[0:3]
	v_mfma_f32_16x16x32_bf16 v[76:79], v[212:215], v[166:169], v[76:79]
	v_mfma_f32_16x16x32_bf16 v[12:15], v[220:223], v[166:169], v[12:15]
	v_mfma_f32_16x16x32_bf16 v[68:71], v[212:215], v[180:183], v[68:71]
	v_mfma_f32_16x16x32_bf16 v[4:7], v[220:223], v[180:183], v[4:7]
	v_mfma_f32_16x16x32_bf16 v[72:75], v[212:215], v[188:191], v[72:75]
	v_mfma_f32_16x16x32_bf16 v[8:11], v[220:223], v[188:191], v[8:11]
	v_mfma_f32_16x16x32_bf16 v[64:67], v[212:215], v[198:201], v[64:67]
	v_mfma_f32_16x16x32_bf16 v[0:3], v[220:223], v[198:201], v[0:3]
	s_add_i32 s83, s83, 2
	s_add_u32 s81, s81, 0x100
	s_addc_u32 s82, s82, 0
	s_cmp_gt_u32 s83, 29
	s_mov_b64 s[62:63], s[64:65]
	s_barrier
	s_cbranch_scc0 .LBB0_173
	v_lshl_or_b32 v158, s70, 7, v150
	v_ashrrev_i32_e32 v159, 31, v158
	v_lshlrev_b64 v[96:97], 2, v[158:159]
	v_lshl_add_u64 v[98:99], s[30:31], 0, v[96:97]
	v_lshl_add_u64 v[100:101], s[46:47], 0, v[96:97]
	v_lshl_add_u64 v[102:103], s[24:25], 0, v[96:97]
	global_load_dwordx4 v[160:163], v[98:99], off
	global_load_dwordx4 v[170:173], v[100:101], off
	v_lshl_add_u64 v[98:99], s[42:43], 0, v[96:97]
	v_lshl_add_u64 v[100:101], s[48:49], 0, v[96:97]
	global_load_dwordx4 v[104:107], v[102:103], off
	global_load_dwordx4 v[164:167], v[98:99], off
	global_load_dwordx4 v[208:211], v[100:101], off
	v_lshl_add_u64 v[100:101], s[50:51], 0, v[96:97]
	global_load_dwordx4 v[212:215], v[100:101], off
	v_lshl_add_u64 v[98:99], s[26:27], 0, v[96:97]
	global_load_dwordx4 v[198:201], v[98:99], off
	v_lshl_add_u64 v[96:97], s[52:53], 0, v[96:97]
	global_load_dwordx4 v[216:219], v[96:97], off
	v_mov_b32_e32 v96, v177
	v_mov_b32_e32 v97, v177
	s_mov_b32 s62, 0xbf317218
	v_mov_b32_dpp v96, v126 row_ror:1 row_mask:0xf bank_mask:0xf
	v_mov_b32_dpp v97, v127 row_ror:1 row_mask:0xf bank_mask:0xf
	s_mov_b32 s34, 0xbfb8aa3b
	v_mov_b32_e32 v100, v177
	v_mov_b32_e32 v101, v177
	v_mov_b32_e32 v224, v177
	v_mov_b32_e32 v225, v177
	v_mov_b32_dpp v100, v138 row_ror:15 row_mask:0xf bank_mask:0xf
	v_mov_b32_dpp v101, v139 row_ror:15 row_mask:0xf bank_mask:0xf
	v_mov_b32_e32 v220, v177
	v_mov_b32_e32 v221, v177
	v_mov_b32_dpp v224, v112 row_ror:1 row_mask:0xf bank_mask:0xf
	v_mov_b32_dpp v225, v113 row_ror:1 row_mask:0xf bank_mask:0xf
	v_mov_b32_dpp v220, v128 row_ror:1 row_mask:0xf bank_mask:0xf
	v_mov_b32_dpp v221, v129 row_ror:1 row_mask:0xf bank_mask:0xf
	v_mov_b32_e32 v222, v177
	v_mov_b32_e32 v223, v177
	v_mov_b32_e32 v108, v177
	v_mov_b32_e32 v180, v177
	v_mov_b32_e32 v109, v177
	v_mov_b32_e32 v181, v177
	v_mov_b32_dpp v222, v140 row_ror:15 row_mask:0xf bank_mask:0xf
	v_mov_b32_dpp v223, v141 row_ror:15 row_mask:0xf bank_mask:0xf
	v_mov_b32_dpp v108, v110 row_ror:1 row_mask:0xf bank_mask:0xf
	v_mov_b32_dpp v180, v122 row_ror:15 row_mask:0xf bank_mask:0xf
	v_mov_b32_dpp v109, v111 row_ror:1 row_mask:0xf bank_mask:0xf
	v_mov_b32_dpp v181, v123 row_ror:15 row_mask:0xf bank_mask:0xf
	v_mov_b32_e32 v226, v177
	v_mov_b32_e32 v227, v177
	v_cmp_gt_i32_e32 vcc, 15, v151
	v_mov_b32_dpp v226, v124 row_ror:15 row_mask:0xf bank_mask:0xf
	v_mov_b32_dpp v227, v125 row_ror:15 row_mask:0xf bank_mask:0xf
	s_mov_b64 s[68:69], -1
	s_waitcnt vmcnt(0)
	v_pk_mul_f32 v[192:193], v[160:161], s[62:63] op_sel_hi:[1,0]
	v_pk_mul_f32 v[168:169], v[172:173], s[34:35] op_sel_hi:[1,0]
	v_pk_mul_f32 v[228:229], v[126:127], v[192:193]
	v_pk_mul_f32 v[194:195], v[162:163], s[62:63] op_sel_hi:[1,0]
	v_pk_mul_f32 v[186:187], v[104:105], s[62:63] op_sel_hi:[1,0]
	v_pk_mul_f32 v[188:189], v[166:167], s[62:63] op_sel_hi:[1,0]
	v_pk_mul_f32 v[172:173], v[210:211], s[34:35] op_sel_hi:[1,0]
	v_pk_mul_f32 v[96:97], v[186:187], v[96:97]
	v_pk_mul_f32 v[166:167], v[214:215], s[34:35] op_sel_hi:[1,0]
	v_pk_mul_f32 v[210:211], v[134:135], v[192:193]
	v_pk_mul_f32 v[214:215], v[130:131], v[192:193]
	v_pk_mul_f32 v[182:183], v[164:165], s[62:63] op_sel_hi:[1,0]
	v_pk_fma_f32 v[96:97], v[138:139], v[192:193], v[96:97]
	v_pk_fma_f32 v[210:211], v[138:139], v[186:187], v[210:211]
	v_pk_fma_f32 v[214:215], v[134:135], v[186:187], v[214:215]
	v_pk_fma_f32 v[228:229], v[130:131], v[186:187], v[228:229]
	v_pk_fma_f32 v[96:97], v[134:135], v[182:183], v[96:97]
	v_pk_fma_f32 v[210:211], v[130:131], v[182:183], v[210:211]
	v_pk_fma_f32 v[214:215], v[126:127], v[182:183], v[214:215]
	v_pk_fma_f32 v[100:101], v[182:183], v[100:101], v[228:229]
	v_pk_mul_f32 v[190:191], v[106:107], s[62:63] op_sel_hi:[1,0]
	v_pk_mul_f32 v[174:175], v[198:199], s[62:63] op_sel_hi:[1,0]
	v_pk_fma_f32 v[96:97], v[198:199], s[62:63], v[96:97] op_sel_hi:[1,0,1]
	v_pk_fma_f32 v[210:211], v[198:199], s[62:63], v[210:211] op_sel_hi:[1,0,1]
	v_pk_fma_f32 v[214:215], v[198:199], s[62:63], v[214:215] op_sel_hi:[1,0,1]
	v_pk_fma_f32 v[100:101], v[198:199], s[62:63], v[100:101] op_sel_hi:[1,0,1]
	v_pk_mul_f32 v[198:199], v[168:169], v[224:225]
	v_pk_mul_f32 v[164:165], v[170:171], s[34:35] op_sel_hi:[1,0]
	v_pk_mul_f32 v[170:171], v[208:209], s[34:35] op_sel_hi:[1,0]
	v_pk_mul_f32 v[162:163], v[212:213], s[34:35] op_sel_hi:[1,0]
	v_pk_mul_f32 v[104:105], v[190:191], v[220:221]
	v_pk_mul_f32 v[208:209], v[136:137], v[194:195]
	v_pk_mul_f32 v[212:213], v[132:133], v[194:195]
	v_pk_mul_f32 v[220:221], v[128:129], v[194:195]
	v_pk_fma_f32 v[198:199], v[124:125], v[172:173], v[198:199]
	v_pk_fma_f32 v[104:105], v[140:141], v[194:195], v[104:105]
	v_pk_fma_f32 v[208:209], v[140:141], v[190:191], v[208:209]
	v_pk_fma_f32 v[212:213], v[136:137], v[190:191], v[212:213]
	v_pk_fma_f32 v[220:221], v[132:133], v[190:191], v[220:221]
	v_pk_fma_f32 v[198:199], v[116:117], v[166:167], v[198:199]
	v_pk_mul_f32 v[232:233], v[110:111], v[170:171]
	v_pk_fma_f32 v[104:105], v[136:137], v[188:189], v[104:105]
	v_pk_fma_f32 v[208:209], v[132:133], v[188:189], v[208:209]
	v_pk_fma_f32 v[212:213], v[128:129], v[188:189], v[212:213]
	v_pk_fma_f32 v[220:221], v[188:189], v[222:223], v[220:221]
	v_pk_fma_f32 v[198:199], v[218:219], s[34:35], v[198:199] op_sel_hi:[1,0,1]
	v_pk_fma_f32 v[232:233], v[118:119], v[164:165], v[232:233]
	v_pk_mul_f32 v[184:185], v[200:201], s[62:63] op_sel_hi:[1,0]
	v_pk_fma_f32 v[104:105], v[200:201], s[62:63], v[104:105] op_sel_hi:[1,0,1]
	v_pk_fma_f32 v[208:209], v[200:201], s[62:63], v[208:209] op_sel_hi:[1,0,1]
	v_pk_fma_f32 v[212:213], v[200:201], s[62:63], v[212:213] op_sel_hi:[1,0,1]
	v_pk_fma_f32 v[200:201], v[200:201], s[62:63], v[220:221] op_sel_hi:[1,0,1]
	v_pk_mul_f32 v[108:109], v[164:165], v[108:109]
	v_pk_mul_f32 v[220:221], v[116:117], v[172:173]
	v_pk_mul_f32 v[222:223], v[114:115], v[170:171]
	v_pk_fma_f32 v[180:181], v[162:163], v[180:181], v[232:233]
	v_exp_f32_e32 v232, v198
	v_exp_f32_e32 v233, v199
	v_pk_fma_f32 v[108:109], v[122:123], v[170:171], v[108:109]
	v_pk_fma_f32 v[220:221], v[124:125], v[168:169], v[220:221]
	v_pk_fma_f32 v[222:223], v[122:123], v[164:165], v[222:223]
	v_pk_mul_f32 v[228:229], v[118:119], v[170:171]
	v_pk_fma_f32 v[108:109], v[114:115], v[162:163], v[108:109]
	v_pk_fma_f32 v[220:221], v[120:121], v[166:167], v[220:221]
	v_pk_fma_f32 v[222:223], v[118:119], v[162:163], v[222:223]
	v_pk_fma_f32 v[228:229], v[114:115], v[164:165], v[228:229]
	v_pk_mul_f32 v[230:231], v[112:113], v[172:173]
	v_pk_fma_f32 v[108:109], v[216:217], s[34:35], v[108:109] op_sel_hi:[1,0,1]
	v_pk_fma_f32 v[220:221], v[218:219], s[34:35], v[220:221] op_sel_hi:[1,0,1]
	v_pk_fma_f32 v[222:223], v[216:217], s[34:35], v[222:223] op_sel_hi:[1,0,1]
	v_pk_fma_f32 v[228:229], v[110:111], v[162:163], v[228:229]
	v_pk_fma_f32 v[230:231], v[120:121], v[168:169], v[230:231]
	v_pk_mul_f32 v[106:107], v[216:217], s[34:35] op_sel_hi:[1,0]
	v_pk_fma_f32 v[228:229], v[216:217], s[34:35], v[228:229] op_sel_hi:[1,0,1]
	v_pk_fma_f32 v[226:227], v[166:167], v[226:227], v[230:231]
	v_exp_f32_e32 v230, v108
	v_exp_f32_e32 v231, v109
	v_pk_fma_f32 v[180:181], v[216:217], s[34:35], v[180:181] op_sel_hi:[1,0,1]
	v_pk_add_f32 v[216:217], v[232:233], 1.0 op_sel_hi:[1,0]
	v_pk_mul_f32 v[104:105], v[104:105], v[198:199]
	v_pk_mul_f32 v[96:97], v[96:97], v[108:109]
	v_exp_f32_e32 v108, v222
	v_exp_f32_e32 v198, v220
	v_exp_f32_e32 v199, v221
	v_exp_f32_e32 v109, v223
	v_pk_mul_f32 v[224:225], v[120:121], v[172:173]
	v_rcp_f32_e32 v216, v216
	v_rcp_f32_e32 v217, v217
	v_pk_fma_f32 v[224:225], v[116:117], v[168:169], v[224:225]
	v_pk_add_f32 v[198:199], v[198:199], 1.0 op_sel_hi:[1,0]
	v_pk_fma_f32 v[224:225], v[112:113], v[166:167], v[224:225]
	v_pk_add_f32 v[108:109], v[108:109], 1.0 op_sel_hi:[1,0]
	v_pk_fma_f32 v[224:225], v[218:219], s[34:35], v[224:225] op_sel_hi:[1,0,1]
	v_pk_mul_f32 v[104:105], v[104:105], v[216:217]
	v_rcp_f32_e32 v108, v108
	v_rcp_f32_e32 v109, v109
	v_rcp_f32_e32 v198, v198
	v_rcp_f32_e32 v199, v199
	v_pk_mul_f32 v[208:209], v[208:209], v[220:221]
	v_exp_f32_e32 v216, v228
	v_exp_f32_e32 v220, v224
	v_exp_f32_e32 v221, v225
	v_exp_f32_e32 v217, v229
	v_pk_mul_f32 v[210:211], v[210:211], v[222:223]
	v_pk_mul_f32 v[160:161], v[218:219], s[34:35] op_sel_hi:[1,0]
	v_pk_fma_f32 v[218:219], v[218:219], s[34:35], v[226:227] op_sel_hi:[1,0,1]
	v_pk_mul_f32 v[198:199], v[208:209], v[198:199]
	v_pk_mul_f32 v[208:209], v[210:211], v[108:109]
	v_pk_add_f32 v[108:109], v[220:221], 1.0 op_sel_hi:[1,0]
	v_pk_add_f32 v[210:211], v[216:217], 1.0 op_sel_hi:[1,0]
	v_rcp_f32_e32 v108, v108
	v_rcp_f32_e32 v210, v210
	v_rcp_f32_e32 v211, v211
	v_rcp_f32_e32 v109, v109
	v_exp_f32_e32 v216, v180
	v_exp_f32_e32 v220, v218
	v_exp_f32_e32 v221, v219
	v_exp_f32_e32 v217, v181
	v_pk_add_f32 v[226:227], v[230:231], 1.0 op_sel_hi:[1,0]
	v_pk_mul_f32 v[212:213], v[212:213], v[224:225]
	v_pk_mul_f32 v[214:215], v[214:215], v[228:229]
	v_rcp_f32_e32 v226, v226
	v_rcp_f32_e32 v227, v227
	v_pk_mul_f32 v[212:213], v[212:213], v[108:109]
	v_pk_mul_f32 v[210:211], v[214:215], v[210:211]
	v_pk_add_f32 v[108:109], v[220:221], 1.0 op_sel_hi:[1,0]
	v_pk_add_f32 v[214:215], v[216:217], 1.0 op_sel_hi:[1,0]
	v_rcp_f32_e32 v108, v108
	v_rcp_f32_e32 v214, v214
	v_rcp_f32_e32 v109, v109
	v_rcp_f32_e32 v215, v215
	v_pk_mul_f32 v[96:97], v[96:97], v[226:227]
	v_pk_mul_f32 v[200:201], v[200:201], v[218:219]
	v_pk_mul_f32 v[100:101], v[100:101], v[180:181]
	v_pk_mul_f32 v[180:181], v[200:201], v[108:109]
	v_pk_mul_f32 v[200:201], v[100:101], v[214:215]
	v_cvt_pk_bf16_f32 v108, v96, v97
	v_cvt_pk_bf16_f32 v109, v104, v105
	v_cvt_pk_bf16_f32 v104, v208, v209
	v_cvt_pk_bf16_f32 v105, v198, v199
	v_cvt_pk_bf16_f32 v100, v210, v211
	v_cvt_pk_bf16_f32 v101, v212, v213
	s_nop 0
	v_cvt_pk_bf16_f32 v96, v200, v201
	v_cvt_pk_bf16_f32 v97, v180, v181
	s_and_saveexec_b64 s[62:63], vcc
	v_cmp_eq_u32_e32 vcc, 0, v151
	s_orn2_b64 s[68:69], vcc, exec
	s_or_b64 exec, exec, s[62:63]
	s_lshl_b32 s34, s79, 2
	s_lshl_b32 s62, s70, 8
	s_add_i32 s64, s34, s38
	s_ashr_i32 s63, s62, 31
	v_lshlrev_b32_e32 v176, 2, v150
	s_mov_b64 s[66:67], exec
	s_and_b64 s[68:69], s[66:67], s[68:69]
	v_mov_b32_e32 v198, 0xbf1f24be
	s_mov_b64 exec, s[68:69]
	s_cbranch_execz .LBB0_178
	s_ashr_i32 s65, s64, 31
	s_lshl_b64 s[68:69], s[64:65], 2
	v_or_b32_e32 v178, s68, v152
	v_mov_b64_e32 v[180:181], s[4:5]
	s_mov_b32 s29, 0xb000
	v_mad_u64_u32 v[180:181], s[70:71], v178, s29, v[180:181]
	v_mad_i32_i24 v181, s69, v204, v181
	v_lshl_add_u64 v[180:181], s[62:63], 2, v[180:181]
	v_lshl_add_u64 v[180:181], v[180:181], 0, v[176:177]
	v_cndmask_b32_e64 v133, v133, v141, s[8:9]
	v_cndmask_b32_e64 v132, v132, v140, s[8:9]
	v_cndmask_b32_e64 v131, v131, v139, s[8:9]
	v_cndmask_b32_e64 v130, v130, v138, s[8:9]
	v_cndmask_b32_e64 v118, v118, v122, s[8:9]
	v_cndmask_b32_e64 v121, v121, v125, s[8:9]
	v_cndmask_b32_e64 v120, v120, v124, s[8:9]
	v_cndmask_b32_e64 v119, v119, v123, s[8:9]
	global_store_dwordx4 v[180:181], v[130:133], off
	global_store_dwordx4 v[180:181], v[118:121], off offset:512
	v_cndmask_b32_e64 v125, v129, v137, s[8:9]
	v_cndmask_b32_e64 v124, v128, v136, s[8:9]
	v_add_co_u32_e32 v118, vcc, s29, v180
	v_cndmask_b32_e64 v123, v127, v135, s[8:9]
	v_cndmask_b32_e64 v122, v126, v134, s[8:9]
	v_addc_co_u32_e32 v119, vcc, 0, v181, vcc
	v_cndmask_b32_e64 v113, v113, v117, s[8:9]
	v_cndmask_b32_e64 v112, v112, v116, s[8:9]
	v_cndmask_b32_e64 v111, v111, v115, s[8:9]
	v_cndmask_b32_e64 v110, v110, v114, s[8:9]
	global_store_dwordx4 v[118:119], v[122:125], off
	global_store_dwordx4 v[118:119], v[110:113], off offset:512
